# adds: GDN prep log-decay scan via DPP; EW-phase chunk gate scalars on 8 waves with DPP scans; mLSTM prep step 3 (Kte, S0) with block LDS reads and select instead of 16 divergent branches
# speedup vs baseline: 1.0335x; 1.0034x over previous
; __device__ __forceinline__ unsigned f2bf(float f) { return pk2(f, 0.f) & 0xffffu; }
; __device__ __forceinline__ float fexp(float x) { return __builtin_amdgcn_exp2f(x * 1.4426950408889634f); }
;     ...
;         for (int i = 0; i < 8; ++i) Vt[(16 * (i & 3) + dg * 2 + (i >> 2)) * 72 + vrow] = (bf16_t)f2bf(CV[vrow * 196 + 128 + dg * 8 + i]);
;         if (w < 2) { const int d = w, p = d ? 63 - lane : lane; float s = gS[d * 64 + p];
; #pragma unroll
;             for (int off = 1; off < 64; off <<= 1) { const float y = __shfl_up(s, off); if (lane >= off) s += y; }
;             gcS[d * 64 + p] = s; if (lane == 63) totS[d] = s;
;             gS[d * 64 + p] = fexp(__shfl(s, 63) - s); }
.LBB0_638:
	s_or_b64 exec, exec, s[10:11]
	s_movk_i32 s0, 0x310
	v_mad_u32_u24 v0, v53, s0, 0
	v_lshl_add_u32 v6, v54, 5, v0
	ds_read_b128 v[2:5], v6 offset:39424
	ds_read_b128 v[6:9], v6 offset:39440
	v_mul_i32_i24_e32 v10, 0xfffffcf2, v53
	s_cmp_lt_i32 s28, 2
	s_cselect_b64 s[10:11], -1, 0
	s_waitcnt lgkmcnt(1)
	v_cvt_pk_bf16_f32 v2, v2, s0
	s_movk_i32 s0, 0x120
	v_mul_lo_u32 v11, v54, s0
	v_add3_u32 v0, v0, v10, v11
	ds_write_b16 v0, v2 offset:27648
	v_cvt_pk_bf16_f32 v2, v3, s0
	ds_write_b16 v0, v2 offset:29952
	v_cvt_pk_bf16_f32 v2, v4, s0
	ds_write_b16 v0, v2 offset:32256
	v_cvt_pk_bf16_f32 v2, v5, s0
	ds_write_b16 v0, v2 offset:34560
	s_waitcnt lgkmcnt(4)
	v_cvt_pk_bf16_f32 v2, v6, s0
	ds_write_b16 v0, v2 offset:27792
	v_cvt_pk_bf16_f32 v2, v7, s0
	ds_write_b16 v0, v2 offset:30096
	v_cvt_pk_bf16_f32 v2, v8, s0
	ds_write_b16 v0, v2 offset:32400
	v_cvt_pk_bf16_f32 v2, v9, s0
	s_cmp_gt_i32 s28, 1
	v_xor_b32_e32 v21, 63, v53
	ds_write_b16 v0, v2 offset:34704
	s_cbranch_scc1 .LBB0_642
	s_cmp_eq_u32 s28, 0
	s_cselect_b64 vcc, -1, 0
	v_cndmask_b32_e32 v0, v21, v53, vcc
	v_lshlrev_b32_e32 v0, 2, v0
	v_lshl_or_b32 v0, s28, 8, v0
	v_add_u32_e32 v0, 0, v0
	ds_read_b32 v2, v0 offset:36864
	s_waitcnt lgkmcnt(0)
	s_nop 1
	v_add_f32_dpp v2, v2, v2 row_shr:1 row_mask:0xf bank_mask:0xf
	s_nop 1
	v_add_f32_dpp v2, v2, v2 row_shr:2 row_mask:0xf bank_mask:0xf
	s_nop 1
	v_add_f32_dpp v2, v2, v2 row_shr:4 row_mask:0xf bank_mask:0xf
	s_nop 1
	v_add_f32_dpp v2, v2, v2 row_shr:8 row_mask:0xf bank_mask:0xf
	s_nop 1
	v_add_f32_dpp v2, v2, v2 row_bcast:15 row_mask:0xa bank_mask:0xf
	s_nop 1
	v_add_f32_dpp v2, v2, v2 row_bcast:31 row_mask:0xc bank_mask:0xf
	v_cmp_eq_u32_e32 vcc, 63, v53
	ds_write_b32 v0, v2 offset:37888
	v_readlane_b32 s1, v2, 63
	s_and_saveexec_b64 s[12:13], vcc
	s_lshl_b32 s0, s28, 2
	s_add_i32 s0, s0, 0
	v_mov_b32_e32 v4, s0
	ds_write_b32 v4, v2 offset:38400
	s_or_b64 exec, exec, s[12:13]
	v_sub_f32_e32 v2, s1, v2
	v_mul_f32_e32 v2, 0x3fb8aa3b, v2
	v_exp_f32_e32 v2, v2
	ds_write_b32 v0, v2 offset:36864

; #define LAS __attribute__((address_space(3)))
; __device__ __forceinline__ unsigned f2bf(float f) { return pk2(f, 0.f) & 0xffffu; }
; __device__ __forceinline__ float fexp(float x) { return __builtin_amdgcn_exp2f(x * 1.4426950408889634f); }
; __device__ __forceinline__ v2u pack4(const f32x4 v) { v2u r; r.x = pk2(v[0], v[1]); r.y = pk2(v[2], v[3]); return r; }
; __device__ __forceinline__ void mlstm_prep_unit(const Frame& F, int l, int u) {
;     ...
;     {
;         const int d = t >> 8, tt = t & 255, p = tt & 63, dg = tt >> 6; const float e = eS[d * 64 + p];
; #pragma unroll
;         for (int i = 0; i < 16; ++i) Kte[d * 4608 + (dg * 16 + i) * 72 + p] = (bf16_t)f2bf(bf2f(Ks[p * 72 + dg * 16 + i]) * e);
; #pragma unroll
;         for (int k2 = 0; k2 < 2; ++k2) { const int tl = 2 * w + k2, mt = tl >> 2, nt = tl & 3;
;             f32x4 acc = {0.f, 0.f, 0.f, 0.f}; acc = mma_ll<2>(Ks + mt * 16 * 72, 72, Qs + nt * 16 * 72, 72, acc, lane);
;             const int n = nt * 16 + lr, m0 = mt * 16 + 4 * lq;
; #pragma unroll
;             for (int dd = 0; dd < 2; ++dd) { const float bn = bS[dd * 64 + n], dn = dmS[dd * 64 + n], rn = rS[dd * 64 + n]; f32x4 sv;
; #pragma unroll
;                 for (int i = 0; i < 4; ++i) { const int m = m0 + i; const bool incl = dd == 0 ? (m <= n) : (m >= n);
;                     const float arg = incl ? (bn - bS[dd * 64 + m] + igS[dd * 64 + m] - dn) : 0.f; sv[i] = incl ? 0.125f * acc[i] * fexp(arg) * rn : 0.f; }
;                 *(LAS v2u*)(S0 + dd * 4608 + n * 72 + m0) = pack4(sv); } }
.LBB0_722:
	v_lshrrev_b32_e32 v4, 8, v2
	v_and_b32_e32 v5, 0xffffff00, v2
	v_lshrrev_b32_e32 v2, 2, v2
	v_and_b32_e32 v2, 48, v2
	s_add_i32 s4, 0, 0x11100
	v_lshlrev_b32_e32 v0, 2, v62
	v_mul_u32_u24_e32 v7, 0x90, v62
	v_lshlrev_b32_e32 v8, 1, v2
	v_add3_u32 v5, s4, v5, v0
	v_add3_u32 v7, 0, v7, v8
	s_waitcnt lgkmcnt(0)
	s_barrier
	v_mbcnt_lo_u32_b32 v74, -1, 0
	v_mbcnt_hi_u32_b32 v74, -1, v74
	v_and_b32_e32 v75, 15, v74
	v_lshrrev_b32_e32 v76, 4, v74
	s_lshr_b32 s8, s3, 2
	s_and_b32 s9, s3, 3
	s_lshl_b32 s22, s8, 8
	s_add_i32 s22, s22, 0x11100
	v_lshl_add_u32 v77, v74, 2, s22
	ds_read_b32 v79, v77
	v_mul_u32_u24_e32 v80, 0x90, v74
	s_lshl_b32 s22, s9, 5
	s_add_i32 s22, s22, 0x2400
	v_add_u32_e32 v80, s22, v80
	ds_read_b128 v[88:91], v80
	ds_read_b128 v[92:95], v80 offset:16
	s_mul_i32 s22, s8, 0x2400
	s_mul_i32 s23, s9, 0x900
	s_add_i32 s22, s22, s23
	s_add_i32 s22, s22, 0x7500
	v_lshl_add_u32 v81, v74, 1, s22
	v_mul_u32_u24_e32 v77, 0x90, v75
	v_lshl_add_u32 v77, v76, 4, v77
	s_lshr_b32 s12, s3, 1
	s_mul_i32 s22, s12, 0x900
	s_add_i32 s22, s22, 0x2400
	v_add_u32_e32 v82, s22, v77
	s_and_b32 s13, s3, 1
	s_lshl_b32 s13, s13, 1
	s_mul_i32 s22, s13, 0x900
	v_add_u32_e32 v83, s22, v77
	ds_read_b128 v[96:99], v82
	ds_read_b128 v[104:107], v83
	ds_read_b128 v[100:103], v82 offset:64
	ds_read_b128 v[108:111], v83 offset:64
	s_waitcnt lgkmcnt(4)
	v_lshlrev_b32_e32 v150, 16, v88
	v_and_b32_e32 v151, 0xffff0000, v88
	v_mul_f32_e32 v150, v79, v150
	v_mul_f32_e32 v151, v79, v151
	v_cvt_pk_bf16_f32 v152, v150, v151
	ds_write_b16 v81, v152
	ds_write_b16_d16_hi v81, v152 offset:144
	v_lshlrev_b32_e32 v150, 16, v89
	v_and_b32_e32 v151, 0xffff0000, v89
	v_mul_f32_e32 v150, v79, v150
	v_mul_f32_e32 v151, v79, v151
	v_cvt_pk_bf16_f32 v152, v150, v151
	ds_write_b16 v81, v152 offset:288
	ds_write_b16_d16_hi v81, v152 offset:432
	v_lshlrev_b32_e32 v150, 16, v90
	v_and_b32_e32 v151, 0xffff0000, v90
	v_mul_f32_e32 v150, v79, v150
	v_mul_f32_e32 v151, v79, v151
	v_cvt_pk_bf16_f32 v152, v150, v151
	ds_write_b16 v81, v152 offset:576
	ds_write_b16_d16_hi v81, v152 offset:720
	v_lshlrev_b32_e32 v150, 16, v91
	v_and_b32_e32 v151, 0xffff0000, v91
	v_mul_f32_e32 v150, v79, v150
	v_mul_f32_e32 v151, v79, v151
	v_cvt_pk_bf16_f32 v152, v150, v151
	ds_write_b16 v81, v152 offset:864
	ds_write_b16_d16_hi v81, v152 offset:1008
	s_waitcnt lgkmcnt(6)
	v_lshlrev_b32_e32 v150, 16, v92
	v_and_b32_e32 v151, 0xffff0000, v92
	v_mul_f32_e32 v150, v79, v150
	v_mul_f32_e32 v151, v79, v151
	v_cvt_pk_bf16_f32 v152, v150, v151
	ds_write_b16 v81, v152 offset:1152
	ds_write_b16_d16_hi v81, v152 offset:1296
	v_lshlrev_b32_e32 v150, 16, v93
	v_and_b32_e32 v151, 0xffff0000, v93
	v_mul_f32_e32 v150, v79, v150
	v_mul_f32_e32 v151, v79, v151
	v_cvt_pk_bf16_f32 v152, v150, v151
	ds_write_b16 v81, v152 offset:1440
	ds_write_b16_d16_hi v81, v152 offset:1584
	v_lshlrev_b32_e32 v150, 16, v94
	v_and_b32_e32 v151, 0xffff0000, v94
	v_mul_f32_e32 v150, v79, v150
	v_mul_f32_e32 v151, v79, v151
	v_cvt_pk_bf16_f32 v152, v150, v151
	ds_write_b16 v81, v152 offset:1728
	ds_write_b16_d16_hi v81, v152 offset:1872
	v_lshlrev_b32_e32 v150, 16, v95
	v_and_b32_e32 v151, 0xffff0000, v95
	v_mul_f32_e32 v150, v79, v150
	v_mul_f32_e32 v151, v79, v151
	v_cvt_pk_bf16_f32 v152, v150, v151
	ds_write_b16 v81, v152 offset:2016
	ds_write_b16_d16_hi v81, v152 offset:2160
	s_waitcnt lgkmcnt(5)
	s_lshl_b32 s22, s13, 4
	v_add_u32_e32 v84, s22, v75
	s_lshl_b32 s22, s12, 4
	v_lshl_add_u32 v78, v76, 2, s22
	v_sub_u32_e32 v85, v84, v78
	v_mul_u32_u24_e32 v86, 0x90, v84
	v_lshl_add_u32 v86, v78, 1, v86
	s_mov_b32 s22, 0x10500
	v_lshl_add_u32 v154, v84, 2, s22
	v_lshl_add_u32 v155, v78, 2, s22
	ds_read_b32 v136, v154 offset:1024
	ds_read_b32 v137, v154 offset:1536
	ds_read_b32 v138, v154 offset:2048
	ds_read_b128 v[120:123], v155 offset:1024
	ds_read_b128 v[128:131], v155
	ds_read_b32 v139, v154 offset:1280
	ds_read_b32 v140, v154 offset:1792
	ds_read_b32 v141, v154 offset:2304
	ds_read_b128 v[124:127], v155 offset:1280
	ds_read_b128 v[132:135], v155 offset:256
	s_waitcnt lgkmcnt(10)
	v_mfma_f32_16x16x32_bf16 v[112:115], v[96:99], v[104:107], 0
	v_mfma_f32_16x16x32_bf16 v[112:115], v[100:103], v[108:111], v[112:115]
	s_waitcnt lgkmcnt(0)
	s_nop 7
	s_nop 1
	v_mul_f32_e32 v116, 0x3e000000, v112
	v_mul_f32_e32 v117, 0x3e000000, v113
	v_mul_f32_e32 v118, 0x3e000000, v114
	v_mul_f32_e32 v119, 0x3e000000, v115
	v_cmp_ge_i32_e64 s[24:25], v85, 0
	v_cmp_ge_i32_e64 s[26:27], v85, 1
	v_cmp_ge_i32_e64 s[28:29], v85, 2
	v_cmp_ge_i32_e64 s[10:11], v85, 3
	v_sub_f32_e32 v158, v136, v120
	v_add_f32_e32 v158, v158, v128
	v_sub_f32_e32 v158, v158, v137
	v_mul_f32_e32 v158, 0x3fb8aa3b, v158
	v_exp_f32_e32 v158, v158
	v_sub_f32_e32 v159, v136, v121
	v_add_f32_e32 v159, v159, v129
	v_sub_f32_e32 v159, v159, v137
	v_mul_f32_e32 v159, 0x3fb8aa3b, v159
	v_exp_f32_e32 v159, v159
	v_sub_f32_e32 v160, v136, v122
	v_add_f32_e32 v160, v160, v130
	v_sub_f32_e32 v160, v160, v137
	v_mul_f32_e32 v160, 0x3fb8aa3b, v160
	v_exp_f32_e32 v160, v160
	v_sub_f32_e32 v161, v136, v123
	v_add_f32_e32 v161, v161, v131
	v_sub_f32_e32 v161, v161, v137
	v_mul_f32_e32 v161, 0x3fb8aa3b, v161
	v_exp_f32_e32 v161, v161
	s_nop 0
	v_mul_f32_e32 v158, v116, v158
	v_mul_f32_e32 v158, v138, v158
	v_cndmask_b32_e64 v144, 0, v158, s[24:25]
	v_mul_f32_e32 v159, v117, v159
	v_mul_f32_e32 v159, v138, v159
	v_cndmask_b32_e64 v145, 0, v159, s[26:27]
	v_mul_f32_e32 v160, v118, v160
	v_mul_f32_e32 v160, v138, v160
	v_cndmask_b32_e64 v146, 0, v160, s[28:29]
	v_mul_f32_e32 v161, v119, v161
	v_mul_f32_e32 v161, v138, v161
	v_cndmask_b32_e64 v147, 0, v161, s[10:11]
	v_cvt_pk_bf16_f32 v148, v144, v145
; #define LAS __attribute__((address_space(3)))
; __device__ __forceinline__ float fexp(float x) { return __builtin_amdgcn_exp2f(x * 1.4426950408889634f); }
; __device__ __forceinline__ v2u pack4(const f32x4 v) { v2u r; r.x = pk2(v[0], v[1]); r.y = pk2(v[2], v[3]); return r; }
; __device__ __forceinline__ void mlstm_prep_unit(const Frame& F, int l, int u) {
;     ...
;         for (int k2 = 0; k2 < 2; ++k2) { const int tl = 2 * w + k2, mt = tl >> 2, nt = tl & 3;
;             f32x4 acc = {0.f, 0.f, 0.f, 0.f}; acc = mma_ll<2>(Ks + mt * 16 * 72, 72, Qs + nt * 16 * 72, 72, acc, lane);
;             const int n = nt * 16 + lr, m0 = mt * 16 + 4 * lq;
; #pragma unroll
;             for (int dd = 0; dd < 2; ++dd) { const float bn = bS[dd * 64 + n], dn = dmS[dd * 64 + n], rn = rS[dd * 64 + n]; f32x4 sv;
; #pragma unroll
;                 for (int i = 0; i < 4; ++i) { const int m = m0 + i; const bool incl = dd == 0 ? (m <= n) : (m >= n);
;                     const float arg = incl ? (bn - bS[dd * 64 + m] + igS[dd * 64 + m] - dn) : 0.f; sv[i] = incl ? 0.125f * acc[i] * fexp(arg) * rn : 0.f; }
;                 *(LAS v2u*)(S0 + dd * 4608 + n * 72 + m0) = pack4(sv); } }
;     ...
;     {
;         const int d = w >> 2, ud = u * 2 + d, q = w & 3; const bool iskv = q >= 2; bf16_t* gdst = F.PM + (size_t)ud * 10240 + (iskv ? 5120 : 0);
; #pragma unroll
;         for (int mm = 0; mm < 2; ++mm) { const int mt = (q & 1) * 2 + mm, m0 = mt * 16 + 4 * lq;
	v_cvt_pk_bf16_f32 v149, v146, v147
	ds_write_b64 v86, v[148:149] offset:48384
	v_cmp_le_i32_e64 s[24:25], v85, 0
	v_cmp_le_i32_e64 s[26:27], v85, 1
	v_cmp_le_i32_e64 s[28:29], v85, 2
	v_cmp_le_i32_e64 s[10:11], v85, 3
	v_sub_f32_e32 v158, v139, v124
	v_add_f32_e32 v158, v158, v132
	v_sub_f32_e32 v158, v158, v140
	v_mul_f32_e32 v158, 0x3fb8aa3b, v158
	v_exp_f32_e32 v158, v158
	v_sub_f32_e32 v159, v139, v125
	v_add_f32_e32 v159, v159, v133
	v_sub_f32_e32 v159, v159, v140
	v_mul_f32_e32 v159, 0x3fb8aa3b, v159
	v_exp_f32_e32 v159, v159
	v_sub_f32_e32 v160, v139, v126
	v_add_f32_e32 v160, v160, v134
	v_sub_f32_e32 v160, v160, v140
	v_mul_f32_e32 v160, 0x3fb8aa3b, v160
	v_exp_f32_e32 v160, v160
	v_sub_f32_e32 v161, v139, v127
	v_add_f32_e32 v161, v161, v135
	v_sub_f32_e32 v161, v161, v140
	v_mul_f32_e32 v161, 0x3fb8aa3b, v161
	v_exp_f32_e32 v161, v161
	s_nop 0
	v_mul_f32_e32 v158, v116, v158
	v_mul_f32_e32 v158, v141, v158
	v_cndmask_b32_e64 v144, 0, v158, s[24:25]
	v_mul_f32_e32 v159, v117, v159
	v_mul_f32_e32 v159, v141, v159
	v_cndmask_b32_e64 v145, 0, v159, s[26:27]
	v_mul_f32_e32 v160, v118, v160
	v_mul_f32_e32 v160, v141, v160
	v_cndmask_b32_e64 v146, 0, v160, s[28:29]
	v_mul_f32_e32 v161, v119, v161
	v_mul_f32_e32 v161, v141, v161
	v_cndmask_b32_e64 v147, 0, v161, s[10:11]
	v_cvt_pk_bf16_f32 v148, v144, v145
	v_cvt_pk_bf16_f32 v149, v146, v147
	ds_write_b64 v86, v[148:149] offset:57600
	s_and_b32 s13, s3, 1
	s_lshl_b32 s13, s13, 1
	s_add_i32 s13, s13, 0x1
	s_mul_i32 s22, s13, 0x900
	v_add_u32_e32 v83, s22, v77
	s_waitcnt lgkmcnt(1)
	ds_read_b128 v[96:99], v82
	ds_read_b128 v[104:107], v83
	ds_read_b128 v[100:103], v82 offset:64
	ds_read_b128 v[108:111], v83 offset:64
	s_lshl_b32 s22, s13, 4
	v_add_u32_e32 v84, s22, v75
	s_lshl_b32 s22, s12, 4
	v_lshl_add_u32 v78, v76, 2, s22
	v_sub_u32_e32 v85, v84, v78
	v_mul_u32_u24_e32 v86, 0x90, v84
	v_lshl_add_u32 v86, v78, 1, v86
	s_mov_b32 s22, 0x10500
	v_lshl_add_u32 v154, v84, 2, s22
	v_lshl_add_u32 v155, v78, 2, s22
	ds_read_b32 v136, v154 offset:1024
	ds_read_b32 v137, v154 offset:1536
	ds_read_b32 v138, v154 offset:2048
	ds_read_b128 v[120:123], v155 offset:1024
	ds_read_b128 v[128:131], v155
	ds_read_b32 v139, v154 offset:1280
	ds_read_b32 v140, v154 offset:1792
	ds_read_b32 v141, v154 offset:2304
	ds_read_b128 v[124:127], v155 offset:1280
	ds_read_b128 v[132:135], v155 offset:256
	s_waitcnt lgkmcnt(10)
	v_mfma_f32_16x16x32_bf16 v[112:115], v[96:99], v[104:107], 0
	v_mfma_f32_16x16x32_bf16 v[112:115], v[100:103], v[108:111], v[112:115]
	s_waitcnt lgkmcnt(0)
	s_nop 7
	s_nop 1
	v_mul_f32_e32 v116, 0x3e000000, v112
	v_mul_f32_e32 v117, 0x3e000000, v113
	v_mul_f32_e32 v118, 0x3e000000, v114
	v_mul_f32_e32 v119, 0x3e000000, v115
	v_cmp_ge_i32_e64 s[24:25], v85, 0
	v_cmp_ge_i32_e64 s[26:27], v85, 1
	v_cmp_ge_i32_e64 s[28:29], v85, 2
	v_cmp_ge_i32_e64 s[10:11], v85, 3
	v_sub_f32_e32 v158, v136, v120
	v_add_f32_e32 v158, v158, v128
	v_sub_f32_e32 v158, v158, v137
	v_mul_f32_e32 v158, 0x3fb8aa3b, v158
	v_exp_f32_e32 v158, v158
	v_sub_f32_e32 v159, v136, v121
	v_add_f32_e32 v159, v159, v129
	v_sub_f32_e32 v159, v159, v137
	v_mul_f32_e32 v159, 0x3fb8aa3b, v159
	v_exp_f32_e32 v159, v159
	v_sub_f32_e32 v160, v136, v122
	v_add_f32_e32 v160, v160, v130
	v_sub_f32_e32 v160, v160, v137
	v_mul_f32_e32 v160, 0x3fb8aa3b, v160
	v_exp_f32_e32 v160, v160
	v_sub_f32_e32 v161, v136, v123
	v_add_f32_e32 v161, v161, v131
	v_sub_f32_e32 v161, v161, v137
	v_mul_f32_e32 v161, 0x3fb8aa3b, v161
	v_exp_f32_e32 v161, v161
	s_nop 0
	v_mul_f32_e32 v158, v116, v158
	v_mul_f32_e32 v158, v138, v158
	v_cndmask_b32_e64 v144, 0, v158, s[24:25]
	v_mul_f32_e32 v159, v117, v159
	v_mul_f32_e32 v159, v138, v159
	v_cndmask_b32_e64 v145, 0, v159, s[26:27]
	v_mul_f32_e32 v160, v118, v160
	v_mul_f32_e32 v160, v138, v160
	v_cndmask_b32_e64 v146, 0, v160, s[28:29]
	v_mul_f32_e32 v161, v119, v161
	v_mul_f32_e32 v161, v138, v161
	v_cndmask_b32_e64 v147, 0, v161, s[10:11]
	v_cvt_pk_bf16_f32 v148, v144, v145
	v_cvt_pk_bf16_f32 v149, v146, v147
	ds_write_b64 v86, v[148:149] offset:48384
	v_cmp_le_i32_e64 s[24:25], v85, 0
	v_cmp_le_i32_e64 s[26:27], v85, 1
	v_cmp_le_i32_e64 s[28:29], v85, 2
	v_cmp_le_i32_e64 s[10:11], v85, 3
	v_sub_f32_e32 v158, v139, v124
	v_add_f32_e32 v158, v158, v132
	v_sub_f32_e32 v158, v158, v140
	v_mul_f32_e32 v158, 0x3fb8aa3b, v158
	v_exp_f32_e32 v158, v158
	v_sub_f32_e32 v159, v139, v125
	v_add_f32_e32 v159, v159, v133
	v_sub_f32_e32 v159, v159, v140
	v_mul_f32_e32 v159, 0x3fb8aa3b, v159
	v_exp_f32_e32 v159, v159
	v_sub_f32_e32 v160, v139, v126
	v_add_f32_e32 v160, v160, v134
	v_sub_f32_e32 v160, v160, v140
	v_mul_f32_e32 v160, 0x3fb8aa3b, v160
	v_exp_f32_e32 v160, v160
	v_sub_f32_e32 v161, v139, v127
	v_add_f32_e32 v161, v161, v135
	v_sub_f32_e32 v161, v161, v140
	v_mul_f32_e32 v161, 0x3fb8aa3b, v161
	v_exp_f32_e32 v161, v161
	s_nop 0
	v_mul_f32_e32 v158, v116, v158
	v_mul_f32_e32 v158, v141, v158
	v_cndmask_b32_e64 v144, 0, v158, s[24:25]
	v_mul_f32_e32 v159, v117, v159
	v_mul_f32_e32 v159, v141, v159
	v_cndmask_b32_e64 v145, 0, v159, s[26:27]
	v_mul_f32_e32 v160, v118, v160
	v_mul_f32_e32 v160, v141, v160
	v_cndmask_b32_e64 v146, 0, v160, s[28:29]
	v_mul_f32_e32 v161, v119, v161
	v_mul_f32_e32 v161, v141, v161
	v_cndmask_b32_e64 v147, 0, v161, s[10:11]
	v_cvt_pk_bf16_f32 v148, v144, v145
	v_cvt_pk_bf16_f32 v149, v146, v147
	ds_write_b64 v86, v[148:149] offset:57600
	s_waitcnt lgkmcnt(0)
	s_lshl_b32 s4, s3, 1
	s_and_b32 s4, s4, 2
	s_mul_i32 s5, s4, 0x900
	s_or_b32 s6, s4, 1
	v_and_b32_e32 v6, 15, v58
	v_mul_u32_u24_e32 v7, 0x90, v6
	v_lshrrev_b32_e32 v2, 1, v58
	v_and_b32_e32 v2, 24, v2
	v_lshlrev_b32_e32 v8, 1, v2
	v_add3_u32 v59, 0, v7, v8
	s_ashr_i32 s7, s3, 2
	s_bitcmp0_b32 s3, 1
	s_cselect_b64 s[20:21], -1, 0
	s_and_b64 s[8:9], s[20:21], exec
	v_readlane_b32 s3, v253, 57
	v_readlane_b32 s8, v253, 58
	s_cselect_b32 s3, s3, s8
	s_mul_i32 s8, s7, 0x2400
	s_add_i32 s3, s3, s8
	v_add3_u32 v2, s3, v7, v8
	v_add_u32_e32 v65, s5, v2
	s_waitcnt lgkmcnt(0)
	s_barrier
; #define LAS __attribute__((address_space(3)))
; __device__ __forceinline__ v2u pack4(const f32x4 v) { v2u r; r.x = pk2(v[0], v[1]); r.y = pk2(v[2], v[3]); return r; }
; __device__ __forceinline__ void mlstm_prep_unit(const Frame& F, int l, int u) {
;     ...
;     {
;         const int d = w >> 2, ud = u * 2 + d, q = w & 3; const bool iskv = q >= 2; bf16_t* gdst = F.PM + (size_t)ud * 10240 + (iskv ? 5120 : 0);
; #pragma unroll
;         for (int mm = 0; mm < 2; ++mm) { const int mt = (q & 1) * 2 + mm, m0 = mt * 16 + 4 * lq;
;             const LAS bf16_t* Aop = (iskv ? Kte : S0) + d * 4608 + mt * 16 * 72;
;             v2u r[5];
; #pragma unroll
;             for (int nt = 0; nt < 5; ++nt) { f32x4 acc = {0.f, 0.f, 0.f, 0.f}; acc = mma_ll<2>(Aop, 72, Vta + nt * 16 * 72, 72, acc, lane);
;                 if (!iskv && nt == 4 && lr == 1) {
; #pragma unroll
;                     for (int i = 0; i < 4; ++i) acc[i] = flS[d * 64 + m0 + i]; }
;                 r[nt] = pack4(acc); }
;             bf16_t* gm = gdst + mt * 1280;
; #pragma unroll
;             for (int pr = 0; pr < 2; ++pr) { v4u o; o.x = r[2 * pr].x; o.y = r[2 * pr].y; o.z = r[2 * pr + 1].x; o.w = r[2 * pr + 1].y; __builtin_nontemporal_store(o, (v4u*)(gm + pr * 512 + lane * 8)); }
;             __builtin_nontemporal_store(r[4], (v2u*)(gm + 1024 + lane * 4)); }
	ds_read_b128 v[66:69], v65
	ds_read_b128 v[70:73], v65 offset:64
	ds_read_b128 v[34:37], v59 offset:18432
	ds_read_b128 v[38:41], v59 offset:18496
	s_waitcnt lgkmcnt(1)
	v_mfma_f32_16x16x32_bf16 v[2:5], v[66:69], v[34:37], 0
	ds_read_b128 v[30:33], v59 offset:20736
	ds_read_b128 v[26:29], v59 offset:20800
	ds_read_b128 v[22:25], v59 offset:23040
	ds_read_b128 v[18:21], v59 offset:23104
	ds_read_b128 v[14:17], v59 offset:25344
	ds_read_b128 v[10:13], v59 offset:25408
	s_waitcnt lgkmcnt(6)
	v_mfma_f32_16x16x32_bf16 v[42:45], v[70:73], v[38:41], v[2:5]
	v_cmp_eq_u32_e32 vcc, 1, v6
	ds_read_b128 v[6:9], v59 offset:27648
	s_lshl_b32 s3, s7, 8
	s_waitcnt lgkmcnt(6)
	v_mfma_f32_16x16x32_bf16 v[2:5], v[66:69], v[30:33], 0
	s_add_i32 s3, s3, 0
	s_add_i32 s3, s3, 0x10f00
	v_and_b32_e32 v58, 48, v58
	s_waitcnt lgkmcnt(5)
	v_mfma_f32_16x16x32_bf16 v[46:49], v[70:73], v[26:29], v[2:5]
	v_add_u32_e32 v63, s3, v58
	s_and_b64 s[10:11], vcc, s[20:21]
	s_waitcnt lgkmcnt(4)
	v_mfma_f32_16x16x32_bf16 v[2:5], v[66:69], v[22:25], 0
	s_waitcnt lgkmcnt(3)
	v_mfma_f32_16x16x32_bf16 v[50:53], v[70:73], v[18:21], v[2:5]
	s_waitcnt lgkmcnt(2)
	v_mfma_f32_16x16x32_bf16 v[2:5], v[66:69], v[14:17], 0
	s_waitcnt lgkmcnt(1)
	v_mfma_f32_16x16x32_bf16 v[54:57], v[70:73], v[10:13], v[2:5]
	s_nop 5
	ds_read_b128 v[2:5], v59 offset:27712
	s_waitcnt lgkmcnt(1)
	v_mfma_f32_16x16x32_bf16 v[66:69], v[66:69], v[6:9], 0
	s_waitcnt lgkmcnt(0)
	v_mfma_f32_16x16x32_bf16 v[58:61], v[70:73], v[2:5], v[66:69]
	s_and_saveexec_b64 s[12:13], s[10:11]
	s_nop 6
	v_lshl_add_u32 v58, s4, 6, v63
	ds_read_b128 v[58:61], v58
	s_or_b64 exec, exec, s[12:13]
	s_lshl_b32 s1, s1, 1
	s_add_i32 s1, s7, s1
	s_mul_hi_i32 s3, s1, 0x5000
	s_mulk_i32 s1, 0x5000
	v_readlane_b32 s5, v254, 46
	s_add_u32 s1, s5, s1
	v_readlane_b32 s5, v254, 47
	s_addc_u32 s3, s5, s3
	s_and_b64 s[8:9], s[20:21], exec
	s_cselect_b32 s5, 0, 0x2800
	s_add_u32 s1, s1, s5
	s_addc_u32 s3, s3, 0
	s_mulk_i32 s4, 0xa00
	s_add_u32 s20, s1, s4
	v_cvt_pk_bf16_f32 v42, v42, v43
	v_cvt_pk_bf16_f32 v43, v44, v45
	v_cvt_pk_bf16_f32 v44, v46, v47
	v_cvt_pk_bf16_f32 v45, v48, v49
	v_cvt_pk_bf16_f32 v47, v52, v53
	s_addc_u32 s21, s3, 0
	v_lshlrev_b32_e32 v52, 4, v62
	v_lshlrev_b32_e32 v64, 3, v62
	v_cvt_pk_bf16_f32 v46, v50, v51
	v_cvt_pk_bf16_f32 v48, v54, v55
	v_cvt_pk_bf16_f32 v49, v56, v57
	s_waitcnt lgkmcnt(0)
	v_cvt_pk_bf16_f32 v50, v58, v59
	v_cvt_pk_bf16_f32 v51, v60, v61
	global_store_dwordx4 v52, v[42:45], s[20:21] nt
	global_store_dwordx4 v52, v[46:49], s[20:21] offset:1024 nt
	global_store_dwordx2 v64, v[50:51], s[20:21] offset:2048 nt
	ds_read_b128 v[42:45], v65 offset:2304
	ds_read_b128 v[46:49], v65 offset:2368
	s_waitcnt lgkmcnt(1)
	v_mfma_f32_16x16x32_bf16 v[34:37], v[42:45], v[34:37], 0
	v_mfma_f32_16x16x32_bf16 v[30:33], v[42:45], v[30:33], 0
	v_mfma_f32_16x16x32_bf16 v[22:25], v[42:45], v[22:25], 0
	v_mfma_f32_16x16x32_bf16 v[14:17], v[42:45], v[14:17], 0
	v_mfma_f32_16x16x32_bf16 v[6:9], v[42:45], v[6:9], 0
	s_waitcnt lgkmcnt(0)
	v_mfma_f32_16x16x32_bf16 v[34:37], v[46:49], v[38:41], v[34:37]
	v_mfma_f32_16x16x32_bf16 v[26:29], v[46:49], v[26:29], v[30:33]
	v_mfma_f32_16x16x32_bf16 v[18:21], v[46:49], v[18:21], v[22:25]
	v_mfma_f32_16x16x32_bf16 v[10:13], v[46:49], v[10:13], v[14:17]
	v_mfma_f32_16x16x32_bf16 v[2:5], v[46:49], v[2:5], v[6:9]
	s_and_saveexec_b64 s[12:13], s[10:11]
	s_cbranch_execz .LBB0_689
	s_nop 5
	v_lshl_add_u32 v2, s6, 6, v63
	ds_read_b128 v[2:5], v2
	s_branch .LBB0_689

; __device__ __forceinline__ float logsigf_(float x) { return x >= 0.f ? -flog1p(fexp(-x)) : x - flog1p(fexp(x)); }
; __device__ __forceinline__ void chs_unit(const Frame& F, int l, int ck) {
;     ...
;     for (int j = 0; j < 2; ++j) { const int idx = t + 512 * j, p = idx >> 4, c = idx & 15, dh = c & 7;
;         const float raw = bf2f(F.Z[(size_t)(row0 + p) * ZW + ZC_LI + c]);
;         G[c * 64 + p] = c < 8 ? raw + F.ig_bias[l * 8 + dh] : logsigf_(raw + F.fg_bias[l * 8 + dh]); }
;     __syncthreads();
;     if (t < 8) { const int d = t >> 2, h = t & 3; float bsum = 0.f, mx = -1e30f;
;         for (int i = 0; i < 64; ++i) { const int p = d ? 63 - i : i; bsum += G[(8 + t) * 64 + p]; mx = fmaxf(mx, G[t * 64 + p] - bsum); }
;         float* o = F.CHS + ((((b * 4 + h) * 2 + d) * 36) + cidx) * 2; o[0] = bsum; o[1] = bsum + mx; }
.LBB0_804:
	s_or_b64 exec, exec, s[12:13]
	v_lshl_add_u32 v0, v9, 2, v8
	v_cmp_gt_i32_e32 vcc, 8, v7
	ds_write_b32 v0, v10
	s_waitcnt lgkmcnt(0)
	s_barrier
	v_readfirstlane_b32 s8, v7
	v_and_b32_e32 v174, 63, v7
	s_nop 1
	s_lshr_b32 s8, s8, 6
	s_lshr_b32 s9, s8, 2
	s_mul_i32 s12, s9, 63
	v_xor_b32_e32 v175, s12, v174
	s_lshl_b32 s12, s8, 8
	v_lshl_add_u32 v175, v175, 2, s12
	ds_read_b32 v177, v175
	ds_read_b32 v176, v175 offset:2048
	s_waitcnt lgkmcnt(0)
	s_nop 1
	v_add_f32_dpp v176, v176, v176 row_shr:1 row_mask:0xf bank_mask:0xf
	s_nop 1
	v_add_f32_dpp v176, v176, v176 row_shr:2 row_mask:0xf bank_mask:0xf
	s_nop 1
	v_add_f32_dpp v176, v176, v176 row_shr:4 row_mask:0xf bank_mask:0xf
	s_nop 1
	v_add_f32_dpp v176, v176, v176 row_shr:8 row_mask:0xf bank_mask:0xf
	s_nop 1
	v_add_f32_dpp v176, v176, v176 row_bcast:15 row_mask:0xa bank_mask:0xf
	s_nop 1
	v_add_f32_dpp v176, v176, v176 row_bcast:31 row_mask:0xc bank_mask:0xf
	v_sub_f32_e32 v177, v177, v176
	s_nop 1
	v_max_f32_dpp v177, v177, v177 row_shr:1 row_mask:0xf bank_mask:0xf
	s_nop 1
	v_max_f32_dpp v177, v177, v177 row_shr:2 row_mask:0xf bank_mask:0xf
	s_nop 1
	v_max_f32_dpp v177, v177, v177 row_shr:4 row_mask:0xf bank_mask:0xf
	s_nop 1
	v_max_f32_dpp v177, v177, v177 row_shr:8 row_mask:0xf bank_mask:0xf
	s_nop 1
	v_max_f32_dpp v177, v177, v177 row_bcast:15 row_mask:0xa bank_mask:0xf
	s_nop 1
	v_max_f32_dpp v177, v177, v177 row_bcast:31 row_mask:0xc bank_mask:0xf
	s_nop 0
	v_readlane_b32 s12, v176, 63
	v_readlane_b32 s13, v177, 63
	s_and_b32 s22, s8, 3
	s_lshl_b32 s22, s22, 1
	s_lshl_b32 s23, s7, 3
	s_or_b32 s22, s22, s23
	s_add_i32 s22, s22, s9
	s_mul_i32 s22, s22, 36
	s_add_i32 s22, s22, s6
	s_lshl_b32 s22, s22, 3
	s_add_u32 s24, s18, s22
	s_addc_u32 s25, s19, 0
	v_mov_b32_e32 v224, s12
	v_add_f32_e32 v225, s13, v224
	s_mov_b64 exec, 1
	s_nop 0
	global_store_dwordx2 v1, v[224:225], s[24:25]
	s_mov_b64 exec, -1
